# v114 + work-queue order: the 1088 GLA-output (G3) units interleaved with the last 128 (smallest) prompt-attention units (groups of 2 prompt + 17 G3) instead of all at the end
# speedup vs baseline: 1.0001x; 1.0001x over previous
; #define WSB(off) (wsp(F) + (off))
; __global__ void __launch_bounds__(NWAVES * 64, 2) hymba_fwd(Args args) {
;     ...
;         for (int it = 0;; ++it) {
;             if (it == 0) __syncthreads();
;             volatile LAS int* slot = (volatile LAS int*)(F.lds + MISC_OFF) + 16 + (it & 1);
;             if (threadIdx.x == 0) *slot = (int)__hip_atomic_fetch_add((unsigned*)(CTL_ + CW_QUEUE + 64 * (l + 4 * rep)), 1u, __ATOMIC_RELAXED, __HIP_MEMORY_SCOPE_AGENT);
;             __syncthreads();
;             const int idx = __builtin_amdgcn_readfirstlane(*slot);
;             if (idx >= 128 + 512 + NCHUNK * 4) break;
;             if (idx < 64) { const int cS = NPCH + (idx >> 2), hS = idx & 3; G1IN_DECL(gS);
;                 gla::g1_load(G1IN_ARGS(gS), cS, hS, ACT_, LOGA_, inp(F, 7) + (size_t)l * 256);
;                 gla::g1_unit<false>(F.lds + RING_OFF, G1IN_ARGS(gS), cS, hS, l, (bf16*)WSB(WS_U), (float*)WSB(WS_D), (bf16*)WSB(WS_OI), (bf16*)WSB(WS_QT), (bf16*)WSB(WS_SC),
;                              inp(F, 4) + (size_t)l * DECB * 4 * 8192, outp(F) + OG_S + (size_t)l * DECB * 4 * 8192, G1IN_ARGS(gS), cS, hS, ACT_, LOGA_, inp(F, 7) + (size_t)l * 256);
;                 CNT_SIGNAL(CTL_ + CW_QUEUE + 64 * l + 32, 1);
;             } else if (idx < 128) { const int b = (idx - 64) >> 2, h = idx & 3;
;                 const float* kc = inp(F, 2) + ((size_t)(l * DECB + b) * PAST) * 512 + h * 128; const float* vc = inp(F, 3) + ((size_t)(l * DECB + b) * PAST) * 512 + h * 128;
;                 const float* kn = outp(F) + OK_S + ((size_t)(l * DECB + b) * 64) * 512 + h * 128; const float* vn = outp(F) + OV_S + ((size_t)(l * DECB + b) * 64) * 512 + h * 128;
;     ...
;                 att::attn_unit_sample(F.lds + RING_OFF, kc, vc, kn, vn, ACT_ + (size_t)(SEQ + 64 * b) * NIN + 1792 + h * 128, MIX_ + (size_t)(SEQ + 64 * b) * DM + 512 + h * 128,
;                                       PAST, h, inp(F, 10) + (size_t)l * 128);
;     ...
;             } else if (idx < 640) { const int i = idx - 128, u = 127 - (i >> 2), h = i & 3;
;     ...
;                 int i2 = i; asm volatile("" : "+s"(i2));
;                 if (att::attn_unit_prompt_t<false>(F.lds + RING_OFF, ACT_ + 2304 + h * 128, ACT_ + 2816 + h * 128, ACT_ + (size_t)(128 * u) * NIN + 1792 + h * 128,
;                                       MIX_ + (size_t)(128 * u) * DM + 512 + h * 128, 2 * u + 2, 128 * u, h, inp(F, 10) + (size_t)l * 128)) {
.LBB0_474:
	s_or_b64 exec, exec, s[0:1]
	v_mov_b32_e32 v3, s10
	s_waitcnt lgkmcnt(0)
	s_barrier
	ds_read_b32 v3, v3
	s_xor_b64 s[8:9], s[96:97], -1
	s_xor_b64 s[12:13], s[84:85], -1
	s_waitcnt lgkmcnt(0)
	v_readfirstlane_b32 s53, v3
	s_cmpk_lt_i32 s53, 0x200
	s_cbranch_scc1 .Lq_noremap
	s_cmpk_gt_i32 s53, 0x6bf
	s_cbranch_scc1 .Lq_noremap
	s_sub_i32 s14, s53, 0x200
	s_mul_hi_u32 s15, s14, 0xd79435f
	s_mul_i32 s16, s15, 19
	s_sub_i32 s16, s14, s16
	s_cmp_lt_u32 s16, 2
	s_cbranch_scc0 .Lq_g3
	s_lshl_b32 s15, s15, 1
	s_add_i32 s53, s15, s16
	s_addk_i32 s53, 0x200
	s_branch .Lq_noremap
.Lq_g3:
	s_mul_i32 s15, s15, 17
	s_add_i32 s53, s15, s16
	s_addk_i32 s53, 0x27e
.Lq_noremap:
	s_cmpk_gt_i32 s53, 0x6bf
	s_cselect_b64 s[44:45], -1, 0
	s_and_b64 vcc, exec, s[44:45]
	s_cbranch_vccnz .LBB0_467
	s_cmp_gt_i32 s53, 63
	s_mov_b64 s[10:11], -1
	s_cbranch_scc0 .LBB0_686
	s_cmpk_gt_u32 s53, 0x7f
	s_cbranch_scc0 .LBB0_631
	s_cmpk_gt_u32 s53, 0x27f
	s_cbranch_scc0 .LBB0_520
	s_add_i32 s20, s53, 0xfffffd80
	s_mov_b64 s[0:1], -1
	s_mov_b64 s[10:11], 0
	s_cmpk_gt_u32 s20, 0x3ff
	s_mov_b64 s[6:7], -1
	s_cbranch_scc0 .LBB0_496
	s_mov_b64 s[6:7], 0
	s_and_b64 vcc, exec, s[12:13]
	s_cbranch_vccz .LBB0_496
	s_and_saveexec_b64 s[10:11], s[38:39]
	s_cbranch_execz .LBB0_495
	v_mov_b32_e32 v3, 0x20258
	s_mov_b32 s21, 1
	v_add_u32_e32 v3, 0, v3
	ds_read_b32 v4, v3
	ds_read_b32 v3, v3 offset:4
	s_waitcnt lgkmcnt(1)
	v_readfirstlane_b32 s12, v4
	s_waitcnt lgkmcnt(0)
	v_readfirstlane_b32 s13, v3
	s_add_u32 s12, s12, 0x4200
	s_addc_u32 s13, s13, 0
	s_branch .LBB0_483
